# removed cg grid.sync at entry (no data seam) and skipped the grid barrier between F2(last layer) and N1 of the next chunk (no dependence)
# baseline (speedup 1.0000x reference)
_Z8mega_fwd4Args:
	s_load_dwordx8 s[4:11], s[0:1], 0x80
	s_mov_b32 s56, s2
	s_load_dword s2, s[0:1], 0xb8
	s_load_dwordx4 s[88:91], s[0:1], 0xa0
	s_load_dwordx2 s[62:63], s[0:1], 0xb0
	v_and_b32_e32 v200, 0x3ff, v0
	s_movk_i32 s3, 0x3ff
	s_waitcnt lgkmcnt(0)
	v_writelane_b32 v253, s4, 0
	v_cmp_gt_u32_e32 vcc, 16, v200
	s_nop 0
	v_writelane_b32 v253, s5, 1
	v_writelane_b32 v253, s6, 2
	v_writelane_b32 v253, s7, 3
	v_writelane_b32 v253, s8, 4
	v_writelane_b32 v253, s9, 5
	v_writelane_b32 v253, s10, 6
	v_writelane_b32 v253, s11, 7
	s_add_u32 s6, s0, 0xb0
	s_addc_u32 s7, s1, 0
	s_and_saveexec_b64 s[4:5], vcc
	v_lshl_add_u32 v1, v200, 2, 0
	v_add_u32_e32 v1, 0x26000, v1
	v_mov_b32_e32 v2, 0
	ds_write_b32 v1, v2
	s_or_b64 exec, exec, s[4:5]
	v_lshrrev_b32_e32 v1, 20, v0
	v_lshrrev_b32_e32 v0, 10, v0
	v_or_b32_e32 v0, v0, v1
	v_and_or_b32 v0, v0, s3, v200
	v_cmp_eq_u32_e32 vcc, 0, v0
	s_waitcnt lgkmcnt(0)
	s_barrier
	s_barrier
	s_load_dwordx16 s[4:19], s[0:1], 0x0
	s_load_dwordx16 s[64:79], s[0:1], 0x40
	s_barrier
	s_waitcnt lgkmcnt(0)
	s_add_u32 s0, s90, 0x180000
	v_writelane_b32 v253, s4, 8
	s_getreg_b32 s3, hwreg(HW_REG_XCC_ID, 0, 4)
	s_addc_u32 s1, s91, 0
	v_writelane_b32 v253, s5, 9
	v_writelane_b32 v253, s6, 10
	v_writelane_b32 v253, s7, 11
	v_writelane_b32 v253, s8, 12
	v_writelane_b32 v253, s9, 13
	v_writelane_b32 v253, s10, 14
	v_writelane_b32 v253, s11, 15
	v_writelane_b32 v253, s12, 16
	v_writelane_b32 v253, s13, 17
	v_writelane_b32 v253, s14, 18
	v_writelane_b32 v253, s15, 19
	v_writelane_b32 v253, s16, 20
	v_writelane_b32 v253, s17, 21
	v_writelane_b32 v253, s18, 22
	v_writelane_b32 v253, s19, 23
	s_and_b32 s12, s3, 15
	s_mov_b32 s5, 0
	s_lshl_b32 s13, s12, 6
	v_cmp_eq_u32_e64 s[8:9], 0, v200
	s_mov_b64 s[6:7], exec
	s_nop 0
	v_writelane_b32 v253, s8, 24
	s_nop 1
	v_writelane_b32 v253, s9, 25
	s_and_b64 s[8:9], s[6:7], s[8:9]
	s_mov_b64 exec, s[8:9]
	s_cbranch_execz .LBB0_15
	s_mov_b64 s[8:9], exec
	v_mbcnt_lo_u32_b32 v0, s8, 0
	v_mbcnt_hi_u32_b32 v0, s9, v0
	v_cmp_eq_u32_e32 vcc, 0, v0
	s_and_b64 s[10:11], exec, vcc
	s_mov_b64 exec, s[10:11]
	s_cbranch_execz .LBB0_15
	s_lshl_b32 s3, s13, 2
	s_bcnt1_i32_b64 s4, s[8:9]
	v_mov_b32_e32 v0, s3
	v_mov_b32_e32 v1, s4
	global_atomic_add v0, v1, s[0:1] offset:1024

.LBB0_372:
	s_waitcnt vmcnt(0)
	s_waitcnt vmcnt(0) lgkmcnt(0)
	s_barrier
	s_mov_b64 s[0:1], exec
	s_cmp_eq_u32 s44, 16
	s_cbranch_scc1 .LBB0_17
	s_cmp_eq_u32 s44, 32
	s_cbranch_scc1 .LBB0_17
	v_readlane_b32 s2, v253, 24
	v_readlane_b32 s3, v253, 25
	s_and_b64 s[2:3], s[0:1], s[2:3]
	s_mov_b64 exec, s[2:3]
	s_cbranch_execz .LBB0_17
	v_readlane_b32 s2, v252, 11
	s_waitcnt vmcnt(0) expcnt(0) lgkmcnt(0)
	s_nop 0
	v_mov_b32_e32 v1, s2
	ds_read_b32 v3, v1
	v_readlane_b32 s2, v252, 12
	s_waitcnt lgkmcnt(0)
	v_cmp_ne_u32_e32 vcc, 0, v3
	v_mov_b32_e32 v1, s2
	ds_read_b32 v2, v1
	s_cbranch_vccnz .LBB0_388
	s_mov_b32 s2, 1
	s_branch .LBB0_376
